# non-temporal (nt) cache policy on the once-read f32 input streams of the prep phase (x rows, weight tiles)
# speedup vs baseline: 1.0008x; 1.0008x over previous
; __device__ __forceinline__ unsigned cvt_pk_bf16(float lo, float hi) { unsigned r; asm("v_cvt_pk_bf16_f32 %0, %1, %2" : "=v"(r) : "v"(lo), "v"(hi)); return r; }
; __device__ __forceinline__ void phase_prep(const Params& p, LAS unsigned char* lds) {
;     ...
;     for (int row = blockIdx.x * 8 + wid; row < T; row += gridDim.x * 16) {
;         const int row2 = row + gridDim.x * 8; const bool has2 = row2 < T;
;         const float* xr = row < TP ? p.x_prompt + (size_t)row * 2048 : p.x_sample + (size_t)(row - TP) * 2048;
;         const float* xr2 = has2 ? (row2 < TP ? p.x_prompt + (size_t)row2 * 2048 : p.x_sample + (size_t)(row2 - TP) * 2048) : xr;
;         f32x4 va[8], vb[8];
; #pragma unroll
;         for (int j = 0; j < 8; ++j) { va[j] = *(const f32x4*)(xr + j * 256 + lane * 4); vb[j] = *(const f32x4*)(xr2 + j * 256 + lane * 4); }
;         float ss = 0.f, ss2 = 0.f;
; #pragma unroll
;         for (int j = 0; j < 8; ++j) {
;             ss += va[j][0] * va[j][0] + va[j][1] * va[j][1] + va[j][2] * va[j][2] + va[j][3] * va[j][3];
;             ss2 += vb[j][0] * vb[j][0] + vb[j][1] * vb[j][1] + vb[j][2] * vb[j][2] + vb[j][3] * vb[j][3];
;             u32x2 w; w.x = cvt_pk_bf16(va[j][0], va[j][1]); w.y = cvt_pk_bf16(va[j][2], va[j][3]);
;             *(u32x2*)(xb + (size_t)row * 2048 + j * 256 + lane * 4) = w;
.LBB0_25:
	s_or_b64 exec, exec, s[14:15]
	v_lshl_add_u64 v[0:1], v[0:1], 0, v[72:73]
	v_lshl_add_u64 v[2:3], v[2:3], 0, v[72:73]
	global_load_dwordx4 v[44:47], v[0:1], off nt
	global_load_dwordx4 v[56:59], v[0:1], off offset:1024 nt
	global_load_dwordx4 v[60:63], v[2:3], off nt
	global_load_dwordx4 v[52:55], v[2:3], off offset:1024 nt
	global_load_dwordx4 v[48:51], v[0:1], off offset:2048 nt
	global_load_dwordx4 v[36:39], v[0:1], off offset:3072 nt
	global_load_dwordx4 v[40:43], v[2:3], off offset:2048 nt
	global_load_dwordx4 v[24:27], v[2:3], off offset:3072 nt
	v_add_co_u32_e32 v0, vcc, s22, v0
	v_lshlrev_b64 v[76:77], 12, v[66:67]
	s_nop 0
	v_addc_co_u32_e32 v1, vcc, 0, v1, vcc
	v_add_co_u32_e32 v2, vcc, s22, v2
	v_ashrrev_i32_e32 v75, 31, v74
	s_nop 0
	v_addc_co_u32_e32 v3, vcc, 0, v3, vcc
	global_load_dwordx4 v[28:31], v[0:1], off nt
	global_load_dwordx4 v[16:19], v[0:1], off offset:1024 nt
	global_load_dwordx4 v[12:15], v[0:1], off offset:2048 nt
	global_load_dwordx4 v[4:7], v[0:1], off offset:3072 nt
	global_load_dwordx4 v[32:35], v[2:3], off nt
	global_load_dwordx4 v[20:23], v[2:3], off offset:1024 nt
	global_load_dwordx4 v[8:11], v[2:3], off offset:2048 nt
	s_nop 0
	global_load_dwordx4 v[0:3], v[2:3], off offset:3072 nt
	v_lshl_add_u64 v[78:79], v[70:71], 0, v[76:77]
	s_waitcnt vmcnt(15)
	v_cvt_pk_bf16_f32 v76, v44, v45
	v_cvt_pk_bf16_f32 v77, v46, v47
	global_store_dwordx2 v[78:79], v[76:77], off
	v_lshlrev_b64 v[76:77], 12, v[74:75]
	v_lshl_add_u64 v[76:77], v[70:71], 0, v[76:77]
	s_and_saveexec_b64 s[14:15], s[6:7]
	s_cbranch_execz .LBB0_27
	s_waitcnt vmcnt(14)
	v_cvt_pk_bf16_f32 v88, v60, v61
	v_cvt_pk_bf16_f32 v89, v62, v63
	global_store_dwordx2 v[76:77], v[88:89], off

; __device__ __forceinline__ void phase_prep(const Params& p, LAS unsigned char* lds) {
;     ...
;     {
;         f32x4 v[8]; float gv[8];
;         int job = blockIdx.x;
;         if (job < DEPTH * 1024) PREP_LOAD(job);
.LBB0_58:
	s_mov_b32 s17, 0
	s_lshl_b32 s2, s2, 6
	s_lshl_b64 s[14:15], s[16:17], 2
	s_add_u32 s0, s0, s14
	v_lshlrev_b32_e32 v0, 4, v82
	s_addc_u32 s1, s1, s15
	v_and_b32_e32 v0, 0x3f0, v0
	s_waitcnt lgkmcnt(0)
	v_mov_b32_e32 v1, 0
	v_add_u32_e32 v4, s2, v81
	v_lshl_add_u64 v[28:29], s[0:1], 0, v[0:1]
	v_mad_i64_i32 v[0:1], s[0:1], s12, v4, 0
	v_lshl_add_u64 v[0:1], v[0:1], 2, v[28:29]
	global_load_dwordx4 v[0:3], v[0:1], off nt
	s_cmp_lg_u64 s[6:7], 0
	s_cselect_b64 s[14:15], -1, 0
	s_cmp_eq_u64 s[6:7], 0
	v_mov_b32_e32 v32, 1.0
	v_mov_b32_e32 v34, 1.0
	s_cbranch_scc1 .LBB0_60
	v_ashrrev_i32_e32 v5, 31, v4
	v_lshl_add_u64 v[4:5], v[4:5], 2, s[6:7]
	global_load_dword v34, v[4:5], off
.LBB0_60:
	v_add_u32_e32 v4, 0x200, v82
	v_ashrrev_i32_e32 v4, 6, v4
	v_add_u32_e32 v8, s2, v4
	v_mad_i64_i32 v[4:5], s[0:1], s12, v8, 0
	v_lshl_add_u64 v[4:5], v[4:5], 2, v[28:29]
	global_load_dwordx4 v[4:7], v[4:5], off nt
	v_cndmask_b32_e64 v9, 0, 1, s[14:15]
	v_cmp_ne_u32_e64 s[0:1], 1, v9
	s_andn2_b64 vcc, exec, s[14:15]
	s_cbranch_vccnz .LBB0_62
	v_ashrrev_i32_e32 v9, 31, v8
	v_lshl_add_u64 v[8:9], v[8:9], 2, s[6:7]
	global_load_dword v32, v[8:9], off
.LBB0_62:
	v_add_u32_e32 v8, 0x400, v82
	v_ashrrev_i32_e32 v8, 6, v8
	v_add_u32_e32 v12, s2, v8
	v_mad_i64_i32 v[8:9], s[14:15], s12, v12, 0
	v_lshl_add_u64 v[8:9], v[8:9], 2, v[28:29]
	global_load_dwordx4 v[8:11], v[8:9], off nt
	v_mov_b32_e32 v36, 1.0
	s_and_b64 vcc, exec, s[0:1]
	v_mov_b32_e32 v38, 1.0
	s_cbranch_vccnz .LBB0_64
	v_ashrrev_i32_e32 v13, 31, v12
	v_lshl_add_u64 v[12:13], v[12:13], 2, s[6:7]
	global_load_dword v38, v[12:13], off
.LBB0_64:
	v_add_u32_e32 v12, 0x600, v82
	v_ashrrev_i32_e32 v12, 6, v12
	v_add_u32_e32 v16, s2, v12
	v_mad_i64_i32 v[12:13], s[14:15], s12, v16, 0
	v_lshl_add_u64 v[12:13], v[12:13], 2, v[28:29]
	global_load_dwordx4 v[12:15], v[12:13], off nt
	s_and_b64 vcc, exec, s[0:1]
	s_cbranch_vccnz .LBB0_66
	v_ashrrev_i32_e32 v17, 31, v16
	v_lshl_add_u64 v[16:17], v[16:17], 2, s[6:7]
	global_load_dword v36, v[16:17], off
.LBB0_66:
	v_add_u32_e32 v16, 0x800, v82
	v_ashrrev_i32_e32 v16, 6, v16
	v_add_u32_e32 v20, s2, v16
	v_mad_i64_i32 v[16:17], s[14:15], s12, v20, 0
	v_lshl_add_u64 v[16:17], v[16:17], 2, v[28:29]
	global_load_dwordx4 v[16:19], v[16:17], off nt
	v_mov_b32_e32 v44, 1.0
	s_and_b64 vcc, exec, s[0:1]
	v_mov_b32_e32 v46, 1.0
	s_cbranch_vccnz .LBB0_68
	v_ashrrev_i32_e32 v21, 31, v20
	v_lshl_add_u64 v[20:21], v[20:21], 2, s[6:7]
	global_load_dword v46, v[20:21], off
.LBB0_68:
	v_add_u32_e32 v20, 0xa00, v82
	v_ashrrev_i32_e32 v20, 6, v20
	v_add_u32_e32 v24, s2, v20
	v_mad_i64_i32 v[20:21], s[14:15], s12, v24, 0
	v_lshl_add_u64 v[20:21], v[20:21], 2, v[28:29]
	global_load_dwordx4 v[20:23], v[20:21], off nt
	s_and_b64 vcc, exec, s[0:1]
	s_cbranch_vccnz .LBB0_70
	v_ashrrev_i32_e32 v25, 31, v24
	v_lshl_add_u64 v[24:25], v[24:25], 2, s[6:7]
	global_load_dword v44, v[24:25], off
.LBB0_70:
	v_add_u32_e32 v24, 0xc00, v82
	v_ashrrev_i32_e32 v24, 6, v24
	v_add_u32_e32 v30, s2, v24
	v_mad_i64_i32 v[24:25], s[14:15], s12, v30, 0
	v_lshl_add_u64 v[24:25], v[24:25], 2, v[28:29]
	global_load_dwordx4 v[24:27], v[24:25], off nt
	v_mov_b32_e32 v48, 1.0
	s_and_b64 vcc, exec, s[0:1]
	v_mov_b32_e32 v50, 1.0
	s_cbranch_vccnz .LBB0_72
	v_ashrrev_i32_e32 v31, 31, v30
	v_lshl_add_u64 v[30:31], v[30:31], 2, s[6:7]
	global_load_dword v50, v[30:31], off
.LBB0_72:
	v_add_u32_e32 v30, 0xe00, v82
	v_ashrrev_i32_e32 v30, 6, v30
	v_add_u32_e32 v40, s2, v30
	v_mad_i64_i32 v[30:31], s[12:13], s12, v40, 0
	v_lshl_add_u64 v[28:29], v[30:31], 2, v[28:29]
	global_load_dwordx4 v[28:31], v[28:29], off nt
	s_and_b64 vcc, exec, s[0:1]
	s_cbranch_vccnz .LBB0_74
	v_ashrrev_i32_e32 v41, 31, v40
	v_lshl_add_u64 v[40:41], v[40:41], 2, s[6:7]
	global_load_dword v48, v[40:41], off

; __device__ __forceinline__ void phase_prep(const Params& p, LAS unsigned char* lds) {
;     ...
;             const int nextjob = job + gridDim.x;
;             if (nextjob < DEPTH * 1024) PREP_LOAD(nextjob);
.LBB0_87:
	s_lshl_b32 s17, s18, 6
	s_lshl_b64 s[18:19], s[4:5], 2
	s_add_u32 s0, s0, s18
	s_addc_u32 s1, s1, s19
	v_add_u32_e32 v4, s17, v81
	v_lshl_add_u64 v[28:29], s[0:1], 0, v[40:41]
	v_mad_i64_i32 v[0:1], s[0:1], s16, v4, 0
	v_lshl_add_u64 v[0:1], v[0:1], 2, v[28:29]
	global_load_dwordx4 v[0:3], v[0:1], off nt
	s_cmp_lg_u64 s[14:15], 0
	s_cselect_b64 s[18:19], -1, 0
	s_cmp_eq_u64 s[14:15], 0
	v_mov_b32_e32 v32, 1.0
	v_mov_b32_e32 v34, 1.0
	s_cbranch_scc1 .LBB0_89
	v_ashrrev_i32_e32 v5, 31, v4
	v_lshl_add_u64 v[4:5], v[4:5], 2, s[14:15]
	global_load_dword v34, v[4:5], off
.LBB0_89:
	v_add_u32_e32 v8, s17, v37
	v_mad_i64_i32 v[4:5], s[0:1], s16, v8, 0
	v_lshl_add_u64 v[4:5], v[4:5], 2, v[28:29]
	global_load_dwordx4 v[4:7], v[4:5], off nt
	v_cndmask_b32_e64 v9, 0, 1, s[18:19]
	v_cmp_ne_u32_e64 s[0:1], 1, v9
	s_andn2_b64 vcc, exec, s[18:19]
	s_cbranch_vccnz .LBB0_91
	v_ashrrev_i32_e32 v9, 31, v8
	v_lshl_add_u64 v[8:9], v[8:9], 2, s[14:15]
	global_load_dword v32, v[8:9], off
.LBB0_91:
	v_add_u32_e32 v12, s17, v39
	v_mad_i64_i32 v[8:9], s[18:19], s16, v12, 0
	v_lshl_add_u64 v[8:9], v[8:9], 2, v[28:29]
	global_load_dwordx4 v[8:11], v[8:9], off nt
	v_mov_b32_e32 v36, 1.0
	s_and_b64 vcc, exec, s[0:1]
	v_mov_b32_e32 v38, 1.0
	s_cbranch_vccnz .LBB0_93
	v_ashrrev_i32_e32 v13, 31, v12
	v_lshl_add_u64 v[12:13], v[12:13], 2, s[14:15]
	global_load_dword v38, v[12:13], off
.LBB0_93:
	v_add_u32_e32 v16, s17, v45
	v_mad_i64_i32 v[12:13], s[18:19], s16, v16, 0
	v_lshl_add_u64 v[12:13], v[12:13], 2, v[28:29]
	global_load_dwordx4 v[12:15], v[12:13], off nt
	s_and_b64 vcc, exec, s[0:1]
	s_cbranch_vccnz .LBB0_95
	v_ashrrev_i32_e32 v17, 31, v16
	v_lshl_add_u64 v[16:17], v[16:17], 2, s[14:15]
	global_load_dword v36, v[16:17], off
.LBB0_95:
	v_add_u32_e32 v20, s17, v47
	v_mad_i64_i32 v[16:17], s[18:19], s16, v20, 0
	v_lshl_add_u64 v[16:17], v[16:17], 2, v[28:29]
	global_load_dwordx4 v[16:19], v[16:17], off nt
	v_mov_b32_e32 v44, 1.0
	s_and_b64 vcc, exec, s[0:1]
	v_mov_b32_e32 v46, 1.0
	s_cbranch_vccnz .LBB0_97
	v_ashrrev_i32_e32 v21, 31, v20
	v_lshl_add_u64 v[20:21], v[20:21], 2, s[14:15]
	global_load_dword v46, v[20:21], off
.LBB0_97:
	v_add_u32_e32 v24, s17, v49
	v_mad_i64_i32 v[20:21], s[18:19], s16, v24, 0
	v_lshl_add_u64 v[20:21], v[20:21], 2, v[28:29]
	global_load_dwordx4 v[20:23], v[20:21], off nt
	s_and_b64 vcc, exec, s[0:1]
	s_cbranch_vccnz .LBB0_99
	v_ashrrev_i32_e32 v25, 31, v24
	v_lshl_add_u64 v[24:25], v[24:25], 2, s[14:15]
	global_load_dword v44, v[24:25], off
.LBB0_99:
	v_add_u32_e32 v30, s17, v51
	v_mad_i64_i32 v[24:25], s[18:19], s16, v30, 0
	v_lshl_add_u64 v[24:25], v[24:25], 2, v[28:29]
	global_load_dwordx4 v[24:27], v[24:25], off nt
	v_mov_b32_e32 v48, 1.0
	s_and_b64 vcc, exec, s[0:1]
	v_mov_b32_e32 v50, 1.0
	s_cbranch_vccnz .LBB0_101
	v_ashrrev_i32_e32 v31, 31, v30
	v_lshl_add_u64 v[30:31], v[30:31], 2, s[14:15]
	global_load_dword v50, v[30:31], off
.LBB0_101:
	v_add_u32_e32 v52, s17, v54
	v_mad_i64_i32 v[30:31], s[16:17], s16, v52, 0
	v_lshl_add_u64 v[28:29], v[30:31], 2, v[28:29]
	global_load_dwordx4 v[28:31], v[28:29], off nt
	s_and_b64 vcc, exec, s[0:1]
	s_cbranch_vccnz .LBB0_76
	v_ashrrev_i32_e32 v53, 31, v52
	v_lshl_add_u64 v[52:53], v[52:53], 2, s[14:15]
	global_load_dword v48, v[52:53], off
	s_branch .LBB0_76
